# MLA attention: second loop copy without running row max when gain bound proves scores small, hand scheduled softmax+PV with exp in place and V fragments read 3 steps ahead
# speedup vs baseline: 1.0450x; 1.0243x over previous
.LBB0_811:
	s_or_b64 exec, exec, s[0:1]
	v_mov_b32_e32 v188, v0
	s_waitcnt lgkmcnt(0)
	s_barrier
	s_cmpk_gt_i32 s2, 0x3ff
	v_readfirstlane_b32 s40, v188
	s_cbranch_scc1 .LBB0_828
	v_ashrrev_i32_e32 v2, 1, v188
	s_movk_i32 s0, 0xffe0
	v_bfe_u32 v4, v188, 5, 1
	v_bfi_b32 v130, s0, v2, v188
	s_movk_i32 s10, 0x600
	v_mov_b64_e32 v[2:3], s[28:29]
	v_mov_b32_e32 v135, 0
	v_mad_i64_i32 v[2:3], s[0:1], v130, s10, v[2:3]
	v_lshlrev_b32_e32 v132, 4, v4
	v_mov_b32_e32 v133, v135
	v_lshl_add_u64 v[136:137], v[2:3], 0, v[132:133]
	v_mbcnt_hi_u32_b32 v2, -1, v254
	v_and_b32_e32 v5, 64, v2
	v_xor_b32_e32 v3, 32, v2
	v_add_u32_e32 v5, 64, v5
	v_cmp_lt_i32_e32 vcc, v3, v5
	s_mov_b32 s0, 0x2aaaaaab
	v_add_u32_e32 v6, 0x200, v188
	v_cndmask_b32_e32 v2, v2, v3, vcc
	v_lshlrev_b32_e32 v190, 2, v2
	v_mul_hi_i32 v2, v188, s0
	v_lshrrev_b32_e32 v3, 31, v2
	v_ashrrev_i32_e32 v2, 1, v2
	v_add_u32_e32 v3, v2, v3
	v_mul_lo_u32 v2, v3, 12
	v_sub_u32_e32 v5, v188, v2
	v_mul_hi_i32 v2, v6, s0
	v_lshrrev_b32_e32 v7, 31, v2
	v_ashrrev_i32_e32 v2, 1, v2
	v_add_u32_e32 v8, v2, v7
	v_mul_lo_u32 v2, v8, 12
	v_sub_u32_e32 v7, v6, v2
	v_add_u32_e32 v2, 0x400, v188
	v_mul_hi_i32 v9, v2, s0
	v_lshrrev_b32_e32 v10, 31, v9
	v_ashrrev_i32_e32 v9, 1, v9
	v_add_u32_e32 v9, v9, v10
	v_mul_lo_u32 v10, v9, 12
	v_sub_u32_e32 v10, v2, v10
	v_lshlrev_b32_e32 v152, 3, v10
	v_ashrrev_i32_e32 v153, 31, v152
	v_lshlrev_b32_e32 v148, 3, v7
	v_ashrrev_i32_e32 v156, 4, v6
	v_lshlrev_b32_e32 v195, 4, v7
	v_lshlrev_b64 v[6:7], 1, v[152:153]
	v_mad_i64_i32 v[142:143], s[6:7], v3, s10, 0
	v_mad_i64_i32 v[146:147], s[6:7], v8, s10, 0
	v_mad_i64_i32 v[150:151], s[6:7], v9, s10, 0
	v_mad_i64_i32 v[6:7], s[6:7], v9, s10, v[6:7]
	v_ashrrev_i32_e32 v149, 31, v148
	s_mov_b64 s[6:7], 0xa400000
	v_lshlrev_b32_e32 v144, 3, v5
	v_lshl_add_u64 v[166:167], v[6:7], 0, s[6:7]
	v_lshlrev_b64 v[6:7], 1, v[148:149]
	v_readlane_b32 s48, v255, 2
	v_ashrrev_i32_e32 v145, 31, v144
	v_mad_i64_i32 v[6:7], s[8:9], v8, s10, v[6:7]
	v_and_b32_e32 v1, 31, v188
	v_lshlrev_b32_e32 v134, 5, v4
	v_readlane_b32 s60, v255, 14
	v_readlane_b32 s61, v255, 15
	v_lshlrev_b32_e32 v2, 3, v188
	v_ashrrev_i32_e32 v154, 4, v188
	s_movk_i32 s0, 0xd0
	v_lshlrev_b32_e32 v192, 4, v5
	v_lshlrev_b32_e32 v5, 4, v188
	v_lshl_add_u64 v[168:169], v[6:7], 0, s[6:7]
	v_lshlrev_b64 v[6:7], 1, v[144:145]
	v_ashrrev_i32_e32 v131, 31, v130
	v_lshlrev_b32_e32 v189, 3, v4
	v_lshl_add_u64 v[138:139], s[60:61], 0, v[134:135]
	v_lshlrev_b32_e32 v134, 6, v4
	v_and_b32_e32 v2, 0x78, v2
	v_ashrrev_i32_e32 v155, 31, v154
	v_ashrrev_i32_e32 v157, 31, v156
	v_mul_lo_u32 v191, v3, s0
	v_mul_lo_u32 v194, v8, s0
	v_mul_lo_u32 v197, v9, s0
	v_lshlrev_b32_e32 v198, 4, v10
	v_and_b32_e32 v200, 0xf0, v5
	s_movk_i32 s0, 0x108
	v_mul_u32_u24_e32 v204, 0xd0, v1
	v_mul_u32_u24_e32 v205, 0x108, v1
	v_lshlrev_b32_e32 v4, 2, v4
	v_and_b32_e32 v1, 15, v188
	v_mad_i64_i32 v[6:7], s[8:9], v3, s10, v[6:7]
	s_mov_b32 s1, 0
	v_lshl_add_u64 v[140:141], s[44:45], 0, v[134:135]
	v_add3_u32 v193, 0, v191, v192
	v_add3_u32 v196, 0, v194, v195
	v_add3_u32 v199, 0, v197, v198
	v_add_u32_e32 v201, 0, v200
	v_mul_lo_u32 v202, v154, s0
	v_mul_lo_u32 v203, v156, s0
	v_lshlrev_b64 v[158:159], 10, v[130:131]
	v_lshlrev_b32_e32 v160, 4, v1
	v_mov_b32_e32 v161, v135
	v_lshlrev_b64 v[162:163], 1, v[154:155]
	v_lshlrev_b64 v[164:165], 1, v[156:157]
	v_lshl_add_u64 v[170:171], v[6:7], 0, s[6:7]
	v_mov_b32_e32 v157, 0x358637bd
	s_mov_b32 s41, 0x800000
	s_movk_i32 s44, 0x6800
	s_mov_b32 s45, 0xff800000
	s_add_u32 s98, s78, 0xd3d0000
	s_addc_u32 s99, s79, 0
	s_mov_b64 s[6:7], 0x100
	s_mov_b64 s[8:9], 0x30000
	v_lshlrev_b32_e32 v134, 1, v4
	v_mov_b32_e32 v206, 0xc0
	v_lshlrev_b32_e32 v172, 1, v2
	v_mov_b32_e32 v207, 0x600
	s_mov_b32 s48, s2
	v_readlane_b32 s49, v255, 3
	v_readlane_b32 s50, v255, 4
	v_readlane_b32 s51, v255, 5
	v_readlane_b32 s52, v255, 6
	v_readlane_b32 s53, v255, 7
	v_readlane_b32 s54, v255, 8
	v_readlane_b32 s55, v255, 9
	v_readlane_b32 s56, v255, 10
	v_readlane_b32 s57, v255, 11
	v_readlane_b32 s58, v255, 12
	v_readlane_b32 s59, v255, 13
	v_readlane_b32 s62, v255, 16
	v_readlane_b32 s63, v255, 17
	v_mbcnt_lo_u32_b32 v236, -1, 0
	v_mbcnt_hi_u32_b32 v236, -1, v236
	v_lshlrev_b32_e32 v236, 2, v236
	global_load_dword v237, v236, s[60:61]
	global_load_dword v238, v236, s[60:61] offset:128
	global_load_dword v240, v236, s[62:63]
	global_load_dword v241, v236, s[62:63] offset:128
	s_waitcnt vmcnt(0)
	v_max_f32_e64 v237, |v237|, |v238|
	v_max_f32_e64 v240, |v240|, |v241|
	v_xor_b32_e32 v238, 4, v236
	ds_bpermute_b32 v241, v238, v237
	ds_bpermute_b32 v242, v238, v240
	s_waitcnt lgkmcnt(0)
	v_max_f32_e32 v237, v237, v241
	v_max_f32_e32 v240, v240, v242
	v_xor_b32_e32 v238, 8, v236
	ds_bpermute_b32 v241, v238, v237
	ds_bpermute_b32 v242, v238, v240
	s_waitcnt lgkmcnt(0)
	v_max_f32_e32 v237, v237, v241
	v_max_f32_e32 v240, v240, v242
	v_xor_b32_e32 v238, 16, v236
	ds_bpermute_b32 v241, v238, v237
	ds_bpermute_b32 v242, v238, v240
	s_waitcnt lgkmcnt(0)
	v_max_f32_e32 v237, v237, v241
	v_max_f32_e32 v240, v240, v242
	v_xor_b32_e32 v238, 32, v236
	ds_bpermute_b32 v241, v238, v237
	ds_bpermute_b32 v242, v238, v240
	s_waitcnt lgkmcnt(0)
	v_max_f32_e32 v237, v237, v241
	v_max_f32_e32 v240, v240, v242
	v_xor_b32_e32 v238, 64, v236
	ds_bpermute_b32 v241, v238, v237
	ds_bpermute_b32 v242, v238, v240
	s_waitcnt lgkmcnt(0)
	v_max_f32_e32 v237, v237, v241
	v_max_f32_e32 v240, v240, v242
	v_xor_b32_e32 v238, 128, v236
	ds_bpermute_b32 v241, v238, v237
	ds_bpermute_b32 v242, v238, v240
	s_waitcnt lgkmcnt(0)
	v_max_f32_e32 v237, v237, v241
	v_max_f32_e32 v240, v240, v242
	v_mul_f32_e32 v237, v237, v240
	s_mov_b32 s100, 0
	v_cmp_gt_f32_e32 vcc, 4.0, v237
	s_nop 3
	s_cmp_lg_u64 vcc, 0
	s_cselect_b32 s100, 1, 0
	s_branch .LBB0_814
.LBB0_813:
	s_barrier
	s_setprio 1
	v_sub_f32_e32 v66, v66, v98
	v_exp_f32_e32 v99, v66
	v_sub_f32_e32 v66, v67, v98
	v_exp_f32_e32 v100, v66
	v_sub_f32_e32 v66, v68, v98
	v_exp_f32_e32 v101, v66
	v_sub_f32_e32 v66, v69, v98
	v_exp_f32_e32 v102, v66
	v_sub_f32_e32 v66, v70, v98
	v_exp_f32_e32 v103, v66
	v_sub_f32_e32 v66, v71, v98
	v_exp_f32_e32 v104, v66
	v_sub_f32_e32 v66, v72, v98
	v_exp_f32_e32 v105, v66
	v_sub_f32_e32 v66, v73, v98
	v_exp_f32_e32 v106, v66
	v_sub_f32_e32 v66, v74, v98
	v_exp_f32_e32 v74, v66
	v_sub_f32_e32 v66, v75, v98
	v_exp_f32_e32 v75, v66
	v_sub_f32_e32 v66, v76, v98
	v_exp_f32_e32 v76, v66
	v_sub_f32_e32 v66, v77, v98
	v_exp_f32_e32 v77, v66
	v_sub_f32_e32 v66, v78, v98
	v_exp_f32_e32 v78, v66
	v_sub_f32_e32 v66, v79, v98
	v_exp_f32_e32 v79, v66
	v_sub_f32_e32 v66, v80, v98
	v_add3_u32 v70, s0, v189, v205
	v_exp_f32_e32 v80, v66
	v_sub_f32_e32 v66, v81, v98
	v_add_u32_e32 v109, 0x6800, v70
	v_exp_f32_e32 v81, v66
	ds_read2_b64 v[66:69], v109 offset1:2
	v_sub_f32_e32 v82, v82, v98
	v_sub_f32_e32 v83, v83, v98
	v_sub_f32_e32 v84, v84, v98
	v_sub_f32_e32 v85, v85, v98
	v_sub_f32_e32 v86, v86, v98
	v_sub_f32_e32 v87, v87, v98
	v_sub_f32_e32 v88, v88, v98
	v_sub_f32_e32 v89, v89, v98
	v_add_u32_e32 v112, 0x8800, v70
	v_exp_f32_e32 v82, v82
	v_exp_f32_e32 v83, v83
	v_exp_f32_e32 v84, v84
	v_exp_f32_e32 v85, v85
	v_exp_f32_e32 v86, v86
	v_exp_f32_e32 v87, v87
	v_exp_f32_e32 v88, v88
	v_exp_f32_e32 v89, v89
	ds_read2_b64 v[70:73], v112 offset0:32 offset1:34
	v_sub_f32_e32 v50, v50, v98
	v_exp_f32_e32 v107, v50
	v_sub_f32_e32 v50, v51, v98
	v_exp_f32_e32 v108, v50
	v_sub_f32_e32 v50, v52, v98
	v_exp_f32_e32 v110, v50
	v_sub_f32_e32 v111, v53, v98
	v_cvt_pk_bf16_f32 v50, v82, v83
	v_cvt_pk_bf16_f32 v51, v84, v85
	v_cvt_pk_bf16_f32 v52, v86, v87
	v_cvt_pk_bf16_f32 v53, v88, v89
	v_sub_f32_e32 v54, v54, v98
	v_exp_f32_e32 v113, v54
	s_waitcnt lgkmcnt(1)
	v_mfma_f32_32x32x16_bf16 v[18:33], v[66:69], v[50:53], v[18:33]
	ds_read2_b64 v[66:69], v109 offset0:4 offset1:6
	v_sub_f32_e32 v54, v55, v98
	v_sub_f32_e32 v90, v90, v98
	v_sub_f32_e32 v91, v91, v98
	v_sub_f32_e32 v92, v92, v98
	v_sub_f32_e32 v93, v93, v98
	v_sub_f32_e32 v94, v94, v98
	v_sub_f32_e32 v95, v95, v98
	v_sub_f32_e32 v96, v96, v98
	v_sub_f32_e32 v97, v97, v98
	v_exp_f32_e32 v114, v54
	v_sub_f32_e32 v54, v56, v98
	v_exp_f32_e32 v90, v90
	v_exp_f32_e32 v91, v91
	v_exp_f32_e32 v92, v92
	v_exp_f32_e32 v93, v93
	v_exp_f32_e32 v94, v94
	v_exp_f32_e32 v95, v95
	v_exp_f32_e32 v96, v96
	v_exp_f32_e32 v97, v97
	s_waitcnt lgkmcnt(1)
	v_mfma_f32_32x32x16_bf16 v[2:17], v[70:73], v[50:53], v[2:17]
	v_exp_f32_e32 v70, v54
	v_sub_f32_e32 v71, v57, v98
	ds_read2_b64 v[54:57], v112 offset0:36 offset1:38
	v_cvt_pk_bf16_f32 v50, v90, v91
	v_cvt_pk_bf16_f32 v51, v92, v93
	v_cvt_pk_bf16_f32 v52, v94, v95
	v_cvt_pk_bf16_f32 v53, v96, v97
	v_sub_f32_e32 v58, v58, v98
	v_exp_f32_e32 v72, v58
	s_waitcnt lgkmcnt(1)
	v_mfma_f32_32x32x16_bf16 v[18:33], v[66:69], v[50:53], v[18:33]
	ds_read2_b64 v[66:69], v109 offset0:8 offset1:10
	v_sub_f32_e32 v58, v59, v98
	v_exp_f32_e32 v73, v58
	v_sub_f32_e32 v58, v60, v98
	v_exp_f32_e32 v115, v58
	v_sub_f32_e32 v58, v61, v98
	v_exp_f32_e32 v111, v111
	s_waitcnt lgkmcnt(1)
	v_mfma_f32_32x32x16_bf16 v[2:17], v[54:57], v[50:53], v[2:17]
	ds_read2_b64 v[54:57], v112 offset0:40 offset1:42
	v_cvt_pk_bf16_f32 v50, v99, v100
	v_cvt_pk_bf16_f32 v51, v101, v102
	v_cvt_pk_bf16_f32 v52, v103, v104
	v_cvt_pk_bf16_f32 v53, v105, v106
	v_exp_f32_e32 v71, v71
	v_sub_f32_e32 v34, v34, v98
	s_waitcnt lgkmcnt(1)
	v_mfma_f32_32x32x16_bf16 v[18:33], v[66:69], v[50:53], v[18:33]
	v_exp_f32_e32 v66, v58
	v_sub_f32_e32 v58, v62, v98
	v_exp_f32_e32 v62, v58
	v_sub_f32_e32 v58, v63, v98
	v_exp_f32_e32 v63, v58
	ds_read2_b64 v[58:61], v109 offset0:12 offset1:14
	v_exp_f32_e32 v67, v34
	s_waitcnt lgkmcnt(1)
	v_mfma_f32_32x32x16_bf16 v[2:17], v[54:57], v[50:53], v[2:17]
	ds_read2_b64 v[54:57], v112 offset0:44 offset1:46
	v_cvt_pk_bf16_f32 v50, v74, v75
	v_cvt_pk_bf16_f32 v51, v76, v77
	v_cvt_pk_bf16_f32 v52, v78, v79
	v_cvt_pk_bf16_f32 v53, v80, v81
	v_sub_f32_e32 v34, v35, v98
	v_exp_f32_e32 v68, v34
	s_waitcnt lgkmcnt(1)
	v_mfma_f32_32x32x16_bf16 v[18:33], v[58:61], v[50:53], v[18:33]
	ds_read2_b64 v[58:61], v109 offset0:16 offset1:18
	v_sub_f32_e32 v34, v36, v98
	v_exp_f32_e32 v69, v34
	v_cvt_pk_bf16_f32 v34, v107, v108
	v_cvt_pk_bf16_f32 v35, v110, v111
	v_cvt_pk_bf16_f32 v36, v113, v114
	v_sub_f32_e32 v38, v38, v98
	s_waitcnt lgkmcnt(1)
	v_mfma_f32_32x32x16_bf16 v[2:17], v[54:57], v[50:53], v[2:17]
	ds_read2_b64 v[50:53], v112 offset0:48 offset1:50
	v_sub_f32_e32 v54, v37, v98
	v_cvt_pk_bf16_f32 v37, v70, v71
	v_sub_f32_e32 v64, v64, v98
	v_sub_f32_e32 v65, v65, v98
	v_exp_f32_e32 v64, v64
	v_exp_f32_e32 v65, v65
	s_waitcnt lgkmcnt(1)
	v_mfma_f32_32x32x16_bf16 v[18:33], v[58:61], v[34:37], v[18:33]
	v_exp_f32_e32 v58, v54
	v_exp_f32_e32 v59, v38
	v_sub_f32_e32 v38, v39, v98
	ds_read2_b64 v[54:57], v109 offset0:20 offset1:22
	v_exp_f32_e32 v60, v38
	v_sub_f32_e32 v38, v40, v98
	v_exp_f32_e32 v61, v38
	s_waitcnt lgkmcnt(1)
	v_mfma_f32_32x32x16_bf16 v[2:17], v[50:53], v[34:37], v[2:17]
	v_sub_f32_e32 v50, v41, v98
	ds_read2_b64 v[38:41], v112 offset0:52 offset1:54
	v_cvt_pk_bf16_f32 v34, v72, v73
	v_cvt_pk_bf16_f32 v35, v115, v66
	v_cvt_pk_bf16_f32 v36, v62, v63
	v_cvt_pk_bf16_f32 v37, v64, v65
	v_sub_f32_e32 v42, v42, v98
	v_sub_f32_e32 v48, v48, v98
	s_waitcnt lgkmcnt(1)
	v_mfma_f32_32x32x16_bf16 v[18:33], v[54:57], v[34:37], v[18:33]
	v_exp_f32_e32 v54, v50
	ds_read2_b64 v[50:53], v109 offset0:24 offset1:26
	v_exp_f32_e32 v55, v42
	v_sub_f32_e32 v42, v43, v98
	v_exp_f32_e32 v56, v42
	v_sub_f32_e32 v42, v44, v98
	v_exp_f32_e32 v57, v42
	s_waitcnt lgkmcnt(1)
	v_mfma_f32_32x32x16_bf16 v[2:17], v[38:41], v[34:37], v[2:17]
	ds_read2_b64 v[38:41], v112 offset0:56 offset1:58
	v_sub_f32_e32 v42, v45, v98
	v_cvt_pk_bf16_f32 v34, v67, v68
	v_cvt_pk_bf16_f32 v35, v69, v58
	v_cvt_pk_bf16_f32 v36, v59, v60
	v_cvt_pk_bf16_f32 v37, v61, v54
	v_exp_f32_e32 v48, v48
	s_lshl_b64 s[10:11], s[10:11], 10
	s_waitcnt lgkmcnt(1)
	v_mfma_f32_32x32x16_bf16 v[18:33], v[50:53], v[34:37], v[18:33]
	v_exp_f32_e32 v50, v42
	v_sub_f32_e32 v42, v46, v98
	v_exp_f32_e32 v46, v42
	v_sub_f32_e32 v42, v47, v98
	v_exp_f32_e32 v47, v42
	ds_read2_b64 v[42:45], v109 offset0:28 offset1:30
	s_add_u32 s0, s36, s10
	s_waitcnt lgkmcnt(1)
	v_mfma_f32_32x32x16_bf16 v[2:17], v[38:41], v[34:37], v[2:17]
	ds_read2_b64 v[38:41], v112 offset0:60 offset1:62
	v_sub_f32_e32 v34, v49, v98
	v_exp_f32_e32 v49, v34
	v_cvt_pk_bf16_f32 v34, v55, v56
	v_cvt_pk_bf16_f32 v35, v57, v50
	v_cvt_pk_bf16_f32 v36, v46, v47
	v_cvt_pk_bf16_f32 v37, v48, v49
	s_addc_u32 s11, s37, s11
	s_lshl_b32 s10, s49, 7
	s_waitcnt lgkmcnt(1)
	v_mfma_f32_32x32x16_bf16 v[18:33], v[42:45], v[34:37], v[18:33]
	s_add_u32 s10, s0, s10
	s_addc_u32 s11, s11, 0
	s_waitcnt lgkmcnt(0)
	s_cmpk_lt_i32 s40, 0x100
	s_cbranch_scc0 .Lmla_fin_nobar
	s_barrier

.Lmla_fin_join:
	v_add_f32_e32 v34, 0, v82
	v_add_f32_e32 v34, v83, v34
	v_add_f32_e32 v34, v84, v34
	v_add_f32_e32 v34, v85, v34
	v_add_f32_e32 v34, v86, v34
	v_add_f32_e32 v34, v87, v34
	v_add_f32_e32 v34, v88, v34
	v_add_f32_e32 v34, v89, v34
	v_add_f32_e32 v34, v90, v34
	v_add_f32_e32 v34, v91, v34
	v_add_f32_e32 v34, v92, v34
	v_add_f32_e32 v34, v93, v34
	v_add_f32_e32 v34, v94, v34
	v_add_f32_e32 v34, v95, v34
	v_add_f32_e32 v34, v96, v34
	v_add_f32_e32 v34, v97, v34
	v_add_f32_e32 v34, v99, v34
	v_add_f32_e32 v34, v100, v34
	v_add_f32_e32 v34, v101, v34
	v_add_f32_e32 v34, v102, v34
	v_add_f32_e32 v34, v103, v34
	v_add_f32_e32 v34, v104, v34
	v_add_f32_e32 v34, v105, v34
	v_add_f32_e32 v34, v106, v34
	v_add_f32_e32 v34, v74, v34
	v_add_f32_e32 v34, v75, v34
	v_add_f32_e32 v34, v76, v34
	v_add_f32_e32 v34, v77, v34
	v_add_f32_e32 v34, v78, v34
	v_add_f32_e32 v34, v79, v34
	v_add_f32_e32 v34, v80, v34
	v_add_f32_e32 v34, v81, v34
	v_add_f32_e32 v34, v107, v34
	v_add_f32_e32 v34, v108, v34
	v_add_f32_e32 v34, v110, v34
	v_add_f32_e32 v34, v111, v34
	v_add_f32_e32 v34, v113, v34
	v_add_f32_e32 v34, v114, v34
	v_add_f32_e32 v34, v70, v34
	v_add_f32_e32 v34, v71, v34
	v_add_f32_e32 v34, v72, v34
	v_add_f32_e32 v34, v73, v34
	v_add_f32_e32 v34, v115, v34
	v_add_f32_e32 v34, v66, v34
	v_add_f32_e32 v34, v62, v34
	v_add_f32_e32 v34, v63, v34
	v_add_f32_e32 v34, v64, v34
	v_add_f32_e32 v34, v65, v34
	v_add_f32_e32 v34, v67, v34
	v_add_f32_e32 v34, v68, v34
	v_add_f32_e32 v34, v69, v34
	v_add_f32_e32 v34, v58, v34
	v_add_f32_e32 v34, v59, v34
	v_add_f32_e32 v34, v60, v34
	v_add_f32_e32 v34, v61, v34
	v_add_f32_e32 v34, v54, v34
	v_add_f32_e32 v34, v55, v34
	v_add_f32_e32 v34, v56, v34
	v_add_f32_e32 v34, v57, v34
	v_add_f32_e32 v34, v50, v34
	v_add_f32_e32 v34, v46, v34
	v_add_f32_e32 v34, v47, v34
	v_add_f32_e32 v34, v48, v34
	v_add_f32_e32 v34, v49, v34
	v_add_f32_e32 v1, v34, v1
	s_setprio 0
	ds_bpermute_b32 v36, v190, v1
	v_lshl_add_u64 v[34:35], s[10:11], 0, v[158:159]
	v_lshl_add_u64 v[34:35], v[34:35], 0, v[134:135]
	s_add_i32 s48, s48, s33
	s_cmpk_gt_i32 s48, 0x3ff
	s_waitcnt lgkmcnt(0)
	v_add_f32_e32 v1, v1, v36
	v_div_scale_f32 v36, s[10:11], v1, v1, 1.0
	v_rcp_f32_e32 v37, v36
	v_div_scale_f32 v38, vcc, 1.0, v1, 1.0
	v_fma_f32 v39, -v36, v37, 1.0
	v_fmac_f32_e32 v37, v39, v37
	v_mul_f32_e32 v39, v38, v37
	v_fma_f32 v40, -v36, v39, v38
	v_fmac_f32_e32 v39, v40, v37
	v_fma_f32 v36, -v36, v39, v38
	v_div_fmas_f32 v36, v36, v37, v39
	v_div_fixup_f32 v36, v36, v1, 1.0
	v_pk_mul_f32 v[18:19], v[18:19], v[36:37] op_sel_hi:[1,0]
	v_pk_mul_f32 v[20:21], v[20:21], v[36:37] op_sel_hi:[1,0]
	v_pk_mul_f32 v[2:3], v[2:3], v[36:37] op_sel_hi:[1,0]
	v_pk_mul_f32 v[4:5], v[4:5], v[36:37] op_sel_hi:[1,0]
	v_cvt_pk_bf16_f32 v18, v18, v19
	v_cvt_pk_bf16_f32 v19, v20, v21
	v_cvt_pk_bf16_f32 v2, v2, v3
	v_cvt_pk_bf16_f32 v3, v4, v5
	global_store_dwordx2 v[34:35], v[18:19], off
	v_pk_mul_f32 v[18:19], v[22:23], v[36:37] op_sel_hi:[1,0]
	v_pk_mul_f32 v[20:21], v[24:25], v[36:37] op_sel_hi:[1,0]
	global_store_dwordx2 v[34:35], v[2:3], off offset:64
	v_pk_mul_f32 v[2:3], v[6:7], v[36:37] op_sel_hi:[1,0]
	v_pk_mul_f32 v[4:5], v[8:9], v[36:37] op_sel_hi:[1,0]
	v_cvt_pk_bf16_f32 v18, v18, v19
	v_cvt_pk_bf16_f32 v19, v20, v21
	v_cvt_pk_bf16_f32 v2, v2, v3
	v_cvt_pk_bf16_f32 v3, v4, v5
	global_store_dwordx2 v[34:35], v[18:19], off offset:16
	v_pk_mul_f32 v[18:19], v[26:27], v[36:37] op_sel_hi:[1,0]
	v_pk_mul_f32 v[20:21], v[28:29], v[36:37] op_sel_hi:[1,0]
	global_store_dwordx2 v[34:35], v[2:3], off offset:80
	v_pk_mul_f32 v[2:3], v[10:11], v[36:37] op_sel_hi:[1,0]
	v_pk_mul_f32 v[4:5], v[12:13], v[36:37] op_sel_hi:[1,0]
	v_cvt_pk_bf16_f32 v18, v18, v19
	v_cvt_pk_bf16_f32 v19, v20, v21
	v_cvt_pk_bf16_f32 v2, v2, v3
	v_cvt_pk_bf16_f32 v3, v4, v5
	global_store_dwordx2 v[34:35], v[18:19], off offset:32
	v_pk_mul_f32 v[18:19], v[30:31], v[36:37] op_sel_hi:[1,0]
	v_pk_mul_f32 v[20:21], v[32:33], v[36:37] op_sel_hi:[1,0]
	global_store_dwordx2 v[34:35], v[2:3], off offset:96
	v_pk_mul_f32 v[2:3], v[14:15], v[36:37] op_sel_hi:[1,0]
	v_pk_mul_f32 v[4:5], v[16:17], v[36:37] op_sel_hi:[1,0]
	v_cvt_pk_bf16_f32 v18, v18, v19
	v_cvt_pk_bf16_f32 v19, v20, v21
	v_cvt_pk_bf16_f32 v2, v2, v3
	v_cvt_pk_bf16_f32 v3, v4, v5
	global_store_dwordx2 v[34:35], v[18:19], off offset:48
	global_store_dwordx2 v[34:35], v[2:3], off offset:112
	s_cbranch_scc1 .LBB0_828

.Lmla_noskew:
	s_cmp_eq_u32 s100, 1
	s_cbranch_scc1 .Lmf_entry
.LBB0_822:
	s_setprio 0
	s_and_b32 s0, 1, s13
	s_cselect_b32 s12, 0, 0xaa00
	s_cselect_b32 s0, 0xaa00, 0
	s_add_i32 s12, s12, 0
	v_lshl_add_u64 v[248:249], s[98:99], 0, v[174:175]
	v_lshl_add_u64 v[250:251], s[98:99], 0, v[176:177]
	v_add3_u32 v236, s0, v191, v192
	v_add3_u32 v237, s0, v194, v195
	global_load_dwordx4 v[240:243], v[248:249], off offset:256
	global_load_dwordx4 v[244:247], v[250:251], off offset:256
	v_add3_u32 v238, s0, v197, v198
	v_add3_u32 v131, s12, v132, v204
	s_waitcnt vmcnt(2)
	ds_write_b128 v236, v[224:227]
	ds_write_b128 v237, v[228:231]
	ds_write_b128 v238, v[232:235]
	ds_read_b128 v[122:125], v131
	ds_read_b128 v[126:129], v131 offset:6656
	ds_read_b128 v[184:187], v131 offset:13312
	ds_read_b128 v[208:211], v131 offset:19968
	ds_read_b128 v[212:215], v131 offset:32
	ds_read_b128 v[216:219], v131 offset:6688
	s_waitcnt lgkmcnt(5)
	v_mfma_f32_32x32x16_bf16 v[82:97], v[122:125], v[102:105], 0
	ds_read_b128 v[122:125], v131 offset:13344
	s_waitcnt lgkmcnt(5)
	v_mfma_f32_32x32x16_bf16 v[66:81], v[126:129], v[102:105], 0
	ds_read_b128 v[126:129], v131 offset:20000
	s_waitcnt lgkmcnt(5)
	v_mfma_f32_32x32x16_bf16 v[50:65], v[184:187], v[102:105], 0
	ds_read_b128 v[184:187], v131 offset:64
	s_waitcnt lgkmcnt(5)
	v_mfma_f32_32x32x16_bf16 v[34:49], v[208:211], v[102:105], 0
	ds_read_b128 v[208:211], v131 offset:6720
	s_waitcnt lgkmcnt(5)
	v_mfma_f32_32x32x16_bf16 v[82:97], v[212:215], v[110:113], v[82:97]
	ds_read_b128 v[212:215], v131 offset:13376
	s_waitcnt lgkmcnt(5)
	v_mfma_f32_32x32x16_bf16 v[66:81], v[216:219], v[110:113], v[66:81]
	ds_read_b128 v[216:219], v131 offset:20032
	s_waitcnt lgkmcnt(5)
	v_mfma_f32_32x32x16_bf16 v[50:65], v[122:125], v[110:113], v[50:65]
	ds_read_b128 v[122:125], v131 offset:96
	s_waitcnt lgkmcnt(5)
	v_mfma_f32_32x32x16_bf16 v[34:49], v[126:129], v[110:113], v[34:49]
	ds_read_b128 v[126:129], v131 offset:6752
	s_waitcnt lgkmcnt(5)
	v_mfma_f32_32x32x16_bf16 v[82:97], v[184:187], v[98:101], v[82:97]
	ds_read_b128 v[184:187], v131 offset:13408
	s_waitcnt lgkmcnt(5)
	v_mfma_f32_32x32x16_bf16 v[66:81], v[208:211], v[98:101], v[66:81]
	ds_read_b128 v[208:211], v131 offset:20064
	s_waitcnt lgkmcnt(5)
	v_mfma_f32_32x32x16_bf16 v[50:65], v[212:215], v[98:101], v[50:65]
	ds_read_b128 v[212:215], v131 offset:128
	s_waitcnt lgkmcnt(5)
	v_mfma_f32_32x32x16_bf16 v[34:49], v[216:219], v[98:101], v[34:49]
	ds_read_b128 v[216:219], v131 offset:6784
	s_waitcnt lgkmcnt(5)
	v_mfma_f32_32x32x16_bf16 v[82:97], v[122:125], v[106:109], v[82:97]
	ds_read_b128 v[122:125], v131 offset:13440
	s_waitcnt lgkmcnt(5)
	v_mfma_f32_32x32x16_bf16 v[66:81], v[126:129], v[106:109], v[66:81]
	ds_read_b128 v[126:129], v131 offset:20096
	s_waitcnt lgkmcnt(5)
	v_mfma_f32_32x32x16_bf16 v[50:65], v[184:187], v[106:109], v[50:65]
	ds_read_b128 v[184:187], v131 offset:160
	s_waitcnt lgkmcnt(5)
	v_mfma_f32_32x32x16_bf16 v[34:49], v[208:211], v[106:109], v[34:49]
	ds_read_b128 v[208:211], v131 offset:6816
	s_waitcnt lgkmcnt(5)
	v_mfma_f32_32x32x16_bf16 v[82:97], v[212:215], v[118:121], v[82:97]
	ds_read_b128 v[212:215], v131 offset:13472
	s_waitcnt lgkmcnt(5)
	v_mfma_f32_32x32x16_bf16 v[66:81], v[216:219], v[118:121], v[66:81]
	ds_read_b128 v[216:219], v131 offset:20128
	s_waitcnt lgkmcnt(5)
	v_mfma_f32_32x32x16_bf16 v[50:65], v[122:125], v[118:121], v[50:65]
	s_waitcnt lgkmcnt(4)
	v_mfma_f32_32x32x16_bf16 v[34:49], v[126:129], v[118:121], v[34:49]
	s_waitcnt lgkmcnt(3)
	v_mfma_f32_32x32x16_bf16 v[82:97], v[184:187], v[114:117], v[82:97]
	s_waitcnt lgkmcnt(2)
	v_mfma_f32_32x32x16_bf16 v[66:81], v[208:211], v[114:117], v[66:81]
	s_waitcnt lgkmcnt(1)
	v_mfma_f32_32x32x16_bf16 v[50:65], v[212:215], v[114:117], v[50:65]
	s_waitcnt lgkmcnt(0)
	v_mfma_f32_32x32x16_bf16 v[34:49], v[216:219], v[114:117], v[34:49]
	s_nop 8
	v_max3_f32 v131, v82, s45, v83
	v_max3_f32 v131, v131, v84, v85
	v_max3_f32 v131, v131, v86, v87
	v_max3_f32 v239, v50, s45, v51
	v_max3_f32 v131, v131, v88, v89
	v_max3_f32 v239, v239, v52, v53
	v_max3_f32 v131, v131, v90, v91
	v_max3_f32 v239, v239, v54, v55
	v_max3_f32 v131, v131, v92, v93
	v_max3_f32 v239, v239, v56, v57
	v_max3_f32 v131, v131, v94, v95
	v_max3_f32 v239, v239, v58, v59
	v_max3_f32 v131, v131, v96, v97
	v_max3_f32 v239, v239, v60, v61
	v_max3_f32 v131, v131, v66, v67
	v_max3_f32 v239, v239, v62, v63
	v_max3_f32 v131, v131, v68, v69
	v_max3_f32 v239, v239, v64, v65
	v_max3_f32 v131, v131, v70, v71
	v_max3_f32 v239, v239, v34, v35
	v_max3_f32 v131, v131, v72, v73
	v_max3_f32 v239, v239, v36, v37
	v_max3_f32 v131, v131, v74, v75
	v_max3_f32 v239, v239, v38, v39
	v_max3_f32 v131, v131, v76, v77
	v_max3_f32 v239, v239, v40, v41
	v_max3_f32 v131, v131, v78, v79
	v_max3_f32 v239, v239, v42, v43
	v_max3_f32 v131, v131, v80, v81
	v_max3_f32 v239, v239, v44, v45
	v_max3_f32 v239, v239, v46, v47
	v_max3_f32 v239, v239, v48, v49
	v_max_f32_e32 v131, v131, v239
	ds_bpermute_b32 v155, v190, v131
	s_waitcnt lgkmcnt(0)
	v_max3_f32 v131, v133, v131, v155
	v_cmp_gt_f32_e32 vcc, v131, v133
	s_cbranch_vccz .LBB0_824
	v_sub_f32_e32 v133, v133, v131
	v_exp_f32_e32 v184, v133
	s_nop 0
	v_pk_mul_f32 v[32:33], v[32:33], v[184:185] op_sel_hi:[1,0]
	v_pk_mul_f32 v[30:31], v[30:31], v[184:185] op_sel_hi:[1,0]
	v_pk_mul_f32 v[28:29], v[28:29], v[184:185] op_sel_hi:[1,0]
	v_pk_mul_f32 v[26:27], v[26:27], v[184:185] op_sel_hi:[1,0]
	v_pk_mul_f32 v[24:25], v[24:25], v[184:185] op_sel_hi:[1,0]
	v_pk_mul_f32 v[22:23], v[22:23], v[184:185] op_sel_hi:[1,0]
	v_pk_mul_f32 v[20:21], v[20:21], v[184:185] op_sel_hi:[1,0]
	v_pk_mul_f32 v[18:19], v[18:19], v[184:185] op_sel_hi:[1,0]
	v_pk_mul_f32 v[16:17], v[16:17], v[184:185] op_sel_hi:[1,0]
	v_pk_mul_f32 v[14:15], v[14:15], v[184:185] op_sel_hi:[1,0]
	v_pk_mul_f32 v[12:13], v[12:13], v[184:185] op_sel_hi:[1,0]
	v_pk_mul_f32 v[10:11], v[10:11], v[184:185] op_sel_hi:[1,0]
	v_pk_mul_f32 v[8:9], v[8:9], v[184:185] op_sel_hi:[1,0]
	v_pk_mul_f32 v[6:7], v[6:7], v[184:185] op_sel_hi:[1,0]
	v_pk_mul_f32 v[4:5], v[4:5], v[184:185] op_sel_hi:[1,0]
	v_pk_mul_f32 v[2:3], v[2:3], v[184:185] op_sel_hi:[1,0]
	v_mul_f32_e32 v1, v1, v184
.LBB0_824:
	s_barrier
	s_setprio 1
	v_sub_f32_e32 v82, v82, v131
	v_exp_f32_e32 v133, v82
	v_sub_f32_e32 v82, v83, v131
	v_exp_f32_e32 v155, v82
	v_sub_f32_e32 v82, v84, v131
	v_exp_f32_e32 v84, v82
	v_sub_f32_e32 v85, v85, v131
	v_exp_f32_e32 v85, v85
	v_sub_f32_e32 v86, v86, v131
	v_add_f32_e32 v173, 0, v133
	v_exp_f32_e32 v86, v86
	v_sub_f32_e32 v87, v87, v131
	v_add_f32_e32 v173, v155, v173
	v_exp_f32_e32 v87, v87
	v_sub_f32_e32 v88, v88, v131
	v_add_f32_e32 v173, v84, v173
	v_exp_f32_e32 v88, v88
	v_sub_f32_e32 v89, v89, v131
	v_add_f32_e32 v173, v85, v173
	v_exp_f32_e32 v89, v89
	v_sub_f32_e32 v90, v90, v131
	v_add_f32_e32 v173, v86, v173
	v_exp_f32_e32 v90, v90
	v_sub_f32_e32 v91, v91, v131
	v_add_f32_e32 v173, v87, v173
	v_exp_f32_e32 v91, v91
	v_sub_f32_e32 v92, v92, v131
	v_add_f32_e32 v173, v88, v173
	v_exp_f32_e32 v92, v92
	v_sub_f32_e32 v93, v93, v131
	v_add_f32_e32 v173, v89, v173
	v_exp_f32_e32 v93, v93
	v_sub_f32_e32 v94, v94, v131
	v_add_f32_e32 v173, v90, v173
	v_exp_f32_e32 v94, v94
	v_sub_f32_e32 v95, v95, v131
	v_add_f32_e32 v173, v91, v173
	v_exp_f32_e32 v95, v95
	v_sub_f32_e32 v96, v96, v131
	v_add_f32_e32 v173, v92, v173
	v_exp_f32_e32 v96, v96
	v_sub_f32_e32 v97, v97, v131
	v_add_f32_e32 v173, v93, v173
	v_exp_f32_e32 v97, v97
	v_sub_f32_e32 v66, v66, v131
	v_add_f32_e32 v173, v94, v173
	v_exp_f32_e32 v208, v66
	v_sub_f32_e32 v66, v67, v131
	v_add_f32_e32 v173, v95, v173
	v_exp_f32_e32 v209, v66
	v_sub_f32_e32 v66, v68, v131
	v_add_f32_e32 v173, v96, v173
	v_exp_f32_e32 v210, v66
	v_sub_f32_e32 v67, v69, v131
	v_add_f32_e32 v66, v97, v173
	v_exp_f32_e32 v173, v67
	v_sub_f32_e32 v67, v70, v131
	v_add_f32_e32 v66, v208, v66
	v_exp_f32_e32 v211, v67
	v_sub_f32_e32 v67, v71, v131
	v_add_f32_e32 v66, v209, v66
	v_exp_f32_e32 v212, v67
	v_sub_f32_e32 v67, v72, v131
	v_add_f32_e32 v66, v210, v66
	v_exp_f32_e32 v213, v67
	v_sub_f32_e32 v67, v73, v131
	v_add_f32_e32 v66, v173, v66
	v_exp_f32_e32 v214, v67
	v_sub_f32_e32 v67, v74, v131
	v_add_f32_e32 v66, v211, v66
	v_exp_f32_e32 v74, v67
	v_sub_f32_e32 v67, v75, v131
	v_add_f32_e32 v66, v212, v66
	v_exp_f32_e32 v75, v67
	v_sub_f32_e32 v67, v76, v131
	v_add_f32_e32 v66, v213, v66
	v_exp_f32_e32 v76, v67
	v_sub_f32_e32 v67, v77, v131
	v_add_f32_e32 v66, v214, v66
	v_exp_f32_e32 v77, v67
	v_sub_f32_e32 v67, v78, v131
	v_add_f32_e32 v66, v74, v66
	v_exp_f32_e32 v78, v67
	v_sub_f32_e32 v67, v79, v131
	v_add_f32_e32 v66, v75, v66
	v_exp_f32_e32 v79, v67
	v_sub_f32_e32 v67, v80, v131
	v_add_f32_e32 v66, v76, v66
	v_exp_f32_e32 v80, v67
	v_sub_f32_e32 v67, v81, v131
	v_add_f32_e32 v66, v77, v66
	v_exp_f32_e32 v81, v67
	v_sub_f32_e32 v50, v50, v131
	v_add_f32_e32 v66, v78, v66
	v_exp_f32_e32 v215, v50
	v_sub_f32_e32 v50, v51, v131
	v_add_f32_e32 v66, v79, v66
	v_exp_f32_e32 v216, v50
	v_sub_f32_e32 v50, v52, v131
	v_add_f32_e32 v66, v80, v66
	v_exp_f32_e32 v217, v50
	v_add_f32_e32 v50, v81, v66
	v_add_f32_e32 v50, v215, v50
	v_add_f32_e32 v50, v216, v50
	v_add_f32_e32 v218, v217, v50
	v_sub_f32_e32 v50, v53, v131
	v_exp_f32_e32 v219, v50
	v_sub_f32_e32 v50, v54, v131
	v_add3_u32 v54, s12, v189, v205
	v_exp_f32_e32 v220, v50
	v_sub_f32_e32 v50, v55, v131
	v_add_u32_e32 v222, 0x6800, v54
	v_exp_f32_e32 v221, v50
	ds_read2_b64 v[50:53], v222 offset1:2
	v_sub_f32_e32 v55, v56, v131
	v_exp_f32_e32 v223, v55
	v_cvt_pk_bf16_f32 v66, v133, v155
	v_cvt_pk_bf16_f32 v67, v84, v85
	v_cvt_pk_bf16_f32 v68, v86, v87
	v_cvt_pk_bf16_f32 v69, v88, v89
	v_add_u32_e32 v84, 0x8800, v54
	ds_read2_b64 v[70:73], v84 offset0:32 offset1:34
	s_waitcnt lgkmcnt(1)
	v_mfma_f32_32x32x16_bf16 v[18:33], v[50:53], v[66:69], v[18:33]
	v_add_f32_e32 v50, v219, v218
	v_add_f32_e32 v50, v220, v50
	v_add_f32_e32 v50, v221, v50
	v_add_f32_e32 v85, v223, v50
	v_sub_f32_e32 v50, v57, v131
	v_exp_f32_e32 v86, v50
	ds_read2_b64 v[50:53], v222 offset0:4 offset1:6
	v_sub_f32_e32 v54, v58, v131
	s_waitcnt lgkmcnt(1)
	v_mfma_f32_32x32x16_bf16 v[2:17], v[70:73], v[66:69], v[2:17]
	v_exp_f32_e32 v70, v54
	v_cvt_pk_bf16_f32 v54, v90, v91
	v_cvt_pk_bf16_f32 v55, v92, v93
	v_cvt_pk_bf16_f32 v56, v94, v95
	v_cvt_pk_bf16_f32 v57, v96, v97
	ds_read2_b64 v[66:69], v84 offset0:36 offset1:38
	v_sub_f32_e32 v34, v34, v131
	s_waitcnt lgkmcnt(1)
	v_mfma_f32_32x32x16_bf16 v[18:33], v[50:53], v[54:57], v[18:33]
	v_add_f32_e32 v50, v86, v85
	v_add_f32_e32 v71, v70, v50
	v_sub_f32_e32 v50, v59, v131
	v_exp_f32_e32 v72, v50
	v_sub_f32_e32 v50, v60, v131
	v_exp_f32_e32 v73, v50
	ds_read2_b64 v[50:53], v222 offset0:8 offset1:10
	s_waitcnt lgkmcnt(1)
	v_mfma_f32_32x32x16_bf16 v[2:17], v[66:69], v[54:57], v[2:17]
	v_sub_f32_e32 v54, v61, v131
	v_exp_f32_e32 v85, v54
	v_cvt_pk_bf16_f32 v54, v208, v209
	v_cvt_pk_bf16_f32 v55, v210, v173
	v_cvt_pk_bf16_f32 v56, v211, v212
	v_cvt_pk_bf16_f32 v57, v213, v214
	ds_read2_b64 v[58:61], v84 offset0:40 offset1:42
	v_lshl_add_u64 v[186:187], s[78:79], 0, v[182:183]
	s_waitcnt lgkmcnt(1)
	v_mfma_f32_32x32x16_bf16 v[18:33], v[50:53], v[54:57], v[18:33]
	v_sub_f32_e32 v50, v62, v131
	v_exp_f32_e32 v87, v50
	v_sub_f32_e32 v50, v63, v131
	v_exp_f32_e32 v88, v50
	v_sub_f32_e32 v50, v64, v131
	v_exp_f32_e32 v89, v50
	ds_read2_b64 v[50:53], v222 offset0:12 offset1:14
	s_waitcnt lgkmcnt(1)
	v_mfma_f32_32x32x16_bf16 v[2:17], v[58:61], v[54:57], v[2:17]
	v_sub_f32_e32 v54, v65, v131
	v_exp_f32_e32 v90, v54
	v_cvt_pk_bf16_f32 v54, v74, v75
	v_cvt_pk_bf16_f32 v55, v76, v77
	v_cvt_pk_bf16_f32 v56, v78, v79
	v_cvt_pk_bf16_f32 v57, v80, v81
	ds_read2_b64 v[58:61], v84 offset0:44 offset1:46
	v_exp_f32_e32 v74, v34
	s_waitcnt lgkmcnt(1)
	v_mfma_f32_32x32x16_bf16 v[18:33], v[50:53], v[54:57], v[18:33]
	ds_read2_b64 v[50:53], v222 offset0:16 offset1:18
	v_sub_f32_e32 v34, v35, v131
	v_exp_f32_e32 v75, v34
	v_sub_f32_e32 v34, v36, v131
	v_exp_f32_e32 v76, v34
	v_sub_f32_e32 v34, v37, v131
	v_exp_f32_e32 v77, v34
	v_cvt_pk_bf16_f32 v34, v215, v216
	v_cvt_pk_bf16_f32 v35, v217, v219
	v_cvt_pk_bf16_f32 v36, v220, v221
	v_cvt_pk_bf16_f32 v37, v223, v86
	v_lshl_add_u64 v[184:185], s[78:79], 0, v[180:181]
	v_lshl_add_u64 v[82:83], s[78:79], 0, v[178:179]
	s_waitcnt lgkmcnt(0)
	v_mfma_f32_32x32x16_bf16 v[18:33], v[50:53], v[34:37], v[18:33]
	global_load_dwordx4 v[224:227], v[186:187], off
	global_load_dwordx4 v[232:235], v[82:83], off
	v_sub_f32_e32 v38, v38, v131
	v_exp_f32_e32 v78, v38
	v_sub_f32_e32 v38, v39, v131
	v_exp_f32_e32 v79, v38
	v_sub_f32_e32 v38, v40, v131
	v_mfma_f32_32x32x16_bf16 v[2:17], v[58:61], v[54:57], v[2:17]
	global_load_dwordx4 v[228:231], v[184:185], off
	ds_read2_b64 v[54:57], v84 offset0:48 offset1:50
	ds_read2_b64 v[66:69], v222 offset0:20 offset1:22
	v_exp_f32_e32 v80, v38
	v_sub_f32_e32 v42, v42, v131
	s_waitcnt lgkmcnt(1)
	v_mfma_f32_32x32x16_bf16 v[2:17], v[54:57], v[34:37], v[2:17]
	v_sub_f32_e32 v34, v41, v131
	ds_read2_b64 v[38:41], v84 offset0:52 offset1:54
	v_exp_f32_e32 v81, v34
	v_cvt_pk_bf16_f32 v34, v70, v72
	v_cvt_pk_bf16_f32 v35, v73, v85
	v_cvt_pk_bf16_f32 v36, v87, v88
	v_cvt_pk_bf16_f32 v37, v89, v90
	ds_read2_b64 v[54:57], v222 offset0:24 offset1:26
	s_add_i32 s0, s0, 0
	s_waitcnt lgkmcnt(2)
	v_mfma_f32_32x32x16_bf16 v[18:33], v[66:69], v[34:37], v[18:33]
	v_exp_f32_e32 v66, v42
	v_sub_f32_e32 v42, v43, v131
	v_exp_f32_e32 v67, v42
	v_sub_f32_e32 v42, v44, v131
	v_exp_f32_e32 v68, v42
	v_sub_f32_e32 v42, v46, v131
	v_exp_f32_e32 v46, v42
	s_waitcnt lgkmcnt(1)
	v_mfma_f32_32x32x16_bf16 v[2:17], v[38:41], v[34:37], v[2:17]
	ds_read2_b64 v[38:41], v84 offset0:56 offset1:58
	v_sub_f32_e32 v42, v47, v131
	v_sub_f32_e32 v34, v45, v131
	v_exp_f32_e32 v47, v42
	v_sub_f32_e32 v42, v48, v131
	v_exp_f32_e32 v69, v34
	v_cvt_pk_bf16_f32 v34, v74, v75
	v_cvt_pk_bf16_f32 v35, v76, v77
	v_cvt_pk_bf16_f32 v36, v78, v79
	v_cvt_pk_bf16_f32 v37, v80, v81
	v_exp_f32_e32 v48, v42
	ds_read2_b64 v[42:45], v222 offset0:28 offset1:30
	s_waitcnt lgkmcnt(2)
	v_mfma_f32_32x32x16_bf16 v[18:33], v[54:57], v[34:37], v[18:33]
	s_add_i32 s13, s13, 1
	v_lshl_add_u64 v[174:175], v[174:175], 0, s[6:7]
	v_lshl_add_u64 v[176:177], v[176:177], 0, s[6:7]
	v_lshl_add_u64 v[178:179], v[178:179], 0, s[8:9]
	v_lshl_add_u64 v[180:181], v[180:181], 0, s[8:9]
	s_cmp_eq_u32 s34, s13
	v_lshl_add_u64 v[182:183], v[182:183], 0, s[8:9]
	s_waitcnt lgkmcnt(1)
	v_mfma_f32_32x32x16_bf16 v[2:17], v[38:41], v[34:37], v[2:17]
	v_sub_f32_e32 v34, v49, v131
	v_exp_f32_e32 v49, v34
	ds_read2_b64 v[38:41], v84 offset0:60 offset1:62
	v_cvt_pk_bf16_f32 v34, v66, v67
	v_cvt_pk_bf16_f32 v35, v68, v69
	v_cvt_pk_bf16_f32 v36, v46, v47
	v_cvt_pk_bf16_f32 v37, v48, v49
	s_waitcnt lgkmcnt(1)
	s_nop 0
	v_mfma_f32_32x32x16_bf16 v[18:33], v[42:45], v[34:37], v[18:33]
	v_add_f32_e32 v42, v72, v71
	v_add_f32_e32 v42, v73, v42
	v_add_f32_e32 v42, v85, v42
	v_add_f32_e32 v42, v87, v42
	v_add_f32_e32 v42, v88, v42
	v_add_f32_e32 v42, v89, v42
	v_add_f32_e32 v42, v90, v42
	s_waitcnt lgkmcnt(0)
	v_mfma_f32_32x32x16_bf16 v[2:17], v[38:41], v[34:37], v[2:17]
	v_add_f32_e32 v34, v74, v42
	v_add_f32_e32 v34, v75, v34
	v_add_f32_e32 v34, v76, v34
	v_add_f32_e32 v34, v77, v34
	v_add_f32_e32 v34, v78, v34
	v_add_f32_e32 v34, v79, v34
	v_add_f32_e32 v34, v80, v34
	v_add_f32_e32 v34, v81, v34
	v_add_f32_e32 v34, v66, v34
	v_add_f32_e32 v34, v67, v34
	v_add_f32_e32 v34, v68, v34
	v_add_f32_e32 v34, v69, v34
	v_add_f32_e32 v34, v46, v34
	v_add_f32_e32 v34, v47, v34
	v_add_f32_e32 v34, v48, v34
	v_add_f32_e32 v34, v49, v34
	v_add_f32_e32 v1, v34, v1
	v_add_u32_e32 v34, s0, v200
	v_add3_u32 v35, v34, v202, s44
	v_add3_u32 v34, v34, v203, s44
	s_waitcnt vmcnt(3)
	ds_write2_b64 v35, v[240:241], v[242:243] offset1:1
	ds_write2_b64 v34, v[244:245], v[246:247] offset1:1
	s_waitcnt lgkmcnt(0)
	s_barrier
	s_cbranch_scc1 .LBB0_826
	v_mov_b32_e32 v133, v131
	s_branch .LBB0_822
.LBB0_826:
	s_setprio 0
	v_add3_u32 v133, s0, v132, v204
	ds_read_b128 v[34:37], v133
	ds_read_b128 v[122:125], v133 offset:32
	s_waitcnt lgkmcnt(1)
	v_mfma_f32_32x32x16_bf16 v[82:97], v[34:37], v[102:105], 0
	ds_read_b128 v[34:37], v133 offset:6656
	ds_read_b128 v[126:129], v133 offset:6688
	s_waitcnt lgkmcnt(1)
	v_mfma_f32_32x32x16_bf16 v[66:81], v[34:37], v[102:105], 0
	ds_read_b128 v[34:37], v133 offset:13312
	ds_read_b128 v[174:177], v133 offset:13344
	s_waitcnt lgkmcnt(1)
	v_mfma_f32_32x32x16_bf16 v[50:65], v[34:37], v[102:105], 0
	ds_read_b128 v[34:37], v133 offset:19968
	ds_read_b128 v[178:181], v133 offset:20000
	s_waitcnt lgkmcnt(1)
	v_mfma_f32_32x32x16_bf16 v[34:49], v[34:37], v[102:105], 0
	v_mfma_f32_32x32x16_bf16 v[82:97], v[122:125], v[110:113], v[82:97]
	v_mfma_f32_32x32x16_bf16 v[66:81], v[126:129], v[110:113], v[66:81]
	v_mfma_f32_32x32x16_bf16 v[50:65], v[174:177], v[110:113], v[50:65]
	s_waitcnt lgkmcnt(0)
	v_mfma_f32_32x32x16_bf16 v[34:49], v[178:181], v[110:113], v[34:49]
	ds_read_b128 v[102:105], v133 offset:64
	ds_read_b128 v[110:113], v133 offset:96
	s_waitcnt lgkmcnt(1)
	v_mfma_f32_32x32x16_bf16 v[82:97], v[102:105], v[98:101], v[82:97]
	ds_read_b128 v[102:105], v133 offset:6720
	ds_read_b128 v[122:125], v133 offset:6752
	s_waitcnt lgkmcnt(1)
	v_mfma_f32_32x32x16_bf16 v[66:81], v[102:105], v[98:101], v[66:81]
	ds_read_b128 v[102:105], v133 offset:13376
	ds_read_b128 v[126:129], v133 offset:13408
	s_waitcnt lgkmcnt(1)
	v_mfma_f32_32x32x16_bf16 v[50:65], v[102:105], v[98:101], v[50:65]
	ds_read_b128 v[102:105], v133 offset:20032
	ds_read_b128 v[174:177], v133 offset:20064
	v_mfma_f32_32x32x16_bf16 v[82:97], v[110:113], v[106:109], v[82:97]
	s_waitcnt lgkmcnt(1)
	v_mfma_f32_32x32x16_bf16 v[34:49], v[102:105], v[98:101], v[34:49]
	ds_read_b128 v[98:101], v133 offset:128
	ds_read_b128 v[102:105], v133 offset:160
	v_mfma_f32_32x32x16_bf16 v[66:81], v[122:125], v[106:109], v[66:81]
	s_waitcnt lgkmcnt(1)
	v_mfma_f32_32x32x16_bf16 v[82:97], v[98:101], v[118:121], v[82:97]
	v_mfma_f32_32x32x16_bf16 v[50:65], v[126:129], v[106:109], v[50:65]
	v_mfma_f32_32x32x16_bf16 v[34:49], v[174:177], v[106:109], v[34:49]
	ds_read_b128 v[98:101], v133 offset:6784
	ds_read_b128 v[106:109], v133 offset:6816
	s_waitcnt lgkmcnt(1)
	v_mfma_f32_32x32x16_bf16 v[66:81], v[98:101], v[118:121], v[66:81]
	ds_read_b128 v[98:101], v133 offset:13440
	ds_read_b128 v[110:113], v133 offset:13472
	v_mfma_f32_32x32x16_bf16 v[82:97], v[102:105], v[114:117], v[82:97]
	s_waitcnt lgkmcnt(1)
	v_mfma_f32_32x32x16_bf16 v[50:65], v[98:101], v[118:121], v[50:65]
	s_nop 9
	v_max3_f32 v122, v82, s45, v83
	v_max3_f32 v122, v122, v84, v85
	v_max3_f32 v122, v122, v86, v87
	ds_read_b128 v[98:101], v133 offset:20096
	ds_read_b128 v[102:105], v133 offset:20128
	v_mfma_f32_32x32x16_bf16 v[66:81], v[106:109], v[114:117], v[66:81]
	v_max3_f32 v106, v122, v88, v89
	v_max3_f32 v106, v106, v90, v91
	v_max3_f32 v106, v106, v92, v93
	v_max3_f32 v106, v106, v94, v95
	v_max3_f32 v106, v106, v96, v97
	s_nop 6
	v_max3_f32 v106, v106, v66, v67
	s_waitcnt lgkmcnt(2)
	v_mfma_f32_32x32x16_bf16 v[50:65], v[110:113], v[114:117], v[50:65]
	v_max3_f32 v106, v106, v68, v69
	v_max3_f32 v106, v106, v70, v71
	v_max3_f32 v106, v106, v72, v73
	v_max3_f32 v106, v106, v74, v75
	v_max3_f32 v106, v106, v76, v77
	v_max3_f32 v106, v106, v78, v79
	v_max3_f32 v106, v106, v80, v81
	s_waitcnt lgkmcnt(1)
	v_mfma_f32_32x32x16_bf16 v[34:49], v[98:101], v[118:121], v[34:49]
	s_nop 2
	v_max3_f32 v106, v106, v50, v51
	v_max3_f32 v98, v106, v52, v53
	v_max3_f32 v98, v98, v54, v55
	v_max3_f32 v98, v98, v56, v57
	v_max3_f32 v98, v98, v58, v59
	v_max3_f32 v98, v98, v60, v61
	v_max3_f32 v98, v98, v62, v63
	s_waitcnt lgkmcnt(0)
	v_mfma_f32_32x32x16_bf16 v[34:49], v[102:105], v[114:117], v[34:49]
	v_max3_f32 v98, v98, v64, v65
	s_nop 10
	v_max3_f32 v98, v98, v34, v35
	v_max3_f32 v98, v98, v36, v37
	v_max3_f32 v98, v98, v38, v39
	v_max3_f32 v98, v98, v40, v41
	v_max3_f32 v98, v98, v42, v43
	v_max3_f32 v98, v98, v44, v45
	v_max3_f32 v98, v98, v46, v47
	v_max3_f32 v98, v98, v48, v49
	ds_bpermute_b32 v99, v190, v98
	s_waitcnt lgkmcnt(0)
	v_max3_f32 v98, v131, v98, v99
	v_cmp_gt_f32_e32 vcc, v98, v131
	s_cbranch_vccz .LBB0_813
	v_sub_f32_e32 v99, v131, v98
	v_exp_f32_e32 v100, v99
	s_nop 0
	v_pk_mul_f32 v[32:33], v[32:33], v[100:101] op_sel_hi:[1,0]
	v_pk_mul_f32 v[30:31], v[30:31], v[100:101] op_sel_hi:[1,0]
	v_pk_mul_f32 v[28:29], v[28:29], v[100:101] op_sel_hi:[1,0]
	v_pk_mul_f32 v[26:27], v[26:27], v[100:101] op_sel_hi:[1,0]
	v_pk_mul_f32 v[24:25], v[24:25], v[100:101] op_sel_hi:[1,0]
	v_pk_mul_f32 v[22:23], v[22:23], v[100:101] op_sel_hi:[1,0]
	v_pk_mul_f32 v[20:21], v[20:21], v[100:101] op_sel_hi:[1,0]
	v_pk_mul_f32 v[18:19], v[18:19], v[100:101] op_sel_hi:[1,0]
	v_pk_mul_f32 v[16:17], v[16:17], v[100:101] op_sel_hi:[1,0]
	v_pk_mul_f32 v[14:15], v[14:15], v[100:101] op_sel_hi:[1,0]
	v_pk_mul_f32 v[12:13], v[12:13], v[100:101] op_sel_hi:[1,0]
	v_pk_mul_f32 v[10:11], v[10:11], v[100:101] op_sel_hi:[1,0]
	v_pk_mul_f32 v[8:9], v[8:9], v[100:101] op_sel_hi:[1,0]
	v_pk_mul_f32 v[6:7], v[6:7], v[100:101] op_sel_hi:[1,0]
	v_pk_mul_f32 v[4:5], v[4:5], v[100:101] op_sel_hi:[1,0]
	v_pk_mul_f32 v[2:3], v[2:3], v[100:101] op_sel_hi:[1,0]
	v_mul_f32_e32 v1, v1, v100
	s_branch .LBB0_813
.Lmf_entry:
	v_mov_b32_e32 v239, 0
.Lmf_loop:
	s_setprio 0
	s_and_b32 s0, 1, s13
	s_cselect_b32 s12, 0, 0xaa00
	s_cselect_b32 s0, 0xaa00, 0
	s_add_i32 s12, s12, 0
	v_lshl_add_u64 v[248:249], s[98:99], 0, v[174:175]
	v_lshl_add_u64 v[250:251], s[98:99], 0, v[176:177]
	v_add3_u32 v236, s0, v191, v192
	v_add3_u32 v237, s0, v194, v195
	global_load_dwordx4 v[240:243], v[248:249], off offset:256
	global_load_dwordx4 v[244:247], v[250:251], off offset:256
	v_add3_u32 v238, s0, v197, v198
	v_add3_u32 v131, s12, v132, v204
	v_add3_u32 v173, s12, v189, v205
	v_add_u32_e32 v155, 0x8800, v173
	v_add_u32_e32 v173, 0x6800, v173
	s_waitcnt vmcnt(2)
	ds_write_b128 v236, v[224:227]
	ds_write_b128 v237, v[228:231]
	ds_write_b128 v238, v[232:235]
	ds_read_b128 v[122:125], v131
	ds_read_b128 v[126:129], v131 offset:6656
	ds_read_b128 v[184:187], v131 offset:13312
	ds_read_b128 v[208:211], v131 offset:19968
	ds_read_b128 v[212:215], v131 offset:32
	ds_read_b128 v[216:219], v131 offset:6688
	s_waitcnt lgkmcnt(5)
	v_mfma_f32_32x32x16_bf16 v[82:97], v[122:125], v[102:105], 0
	ds_read_b128 v[122:125], v131 offset:13344
	s_waitcnt lgkmcnt(5)
	v_mfma_f32_32x32x16_bf16 v[66:81], v[126:129], v[102:105], 0
	ds_read_b128 v[126:129], v131 offset:20000
	s_waitcnt lgkmcnt(5)
	v_mfma_f32_32x32x16_bf16 v[50:65], v[184:187], v[102:105], 0
	ds_read_b128 v[184:187], v131 offset:64
	s_waitcnt lgkmcnt(5)
	v_mfma_f32_32x32x16_bf16 v[34:49], v[208:211], v[102:105], 0
	ds_read_b128 v[208:211], v131 offset:6720
	s_waitcnt lgkmcnt(5)
	v_mfma_f32_32x32x16_bf16 v[82:97], v[212:215], v[110:113], v[82:97]
	ds_read_b128 v[212:215], v131 offset:13376
	s_waitcnt lgkmcnt(5)
	v_mfma_f32_32x32x16_bf16 v[66:81], v[216:219], v[110:113], v[66:81]
	ds_read_b128 v[216:219], v131 offset:20032
	s_waitcnt lgkmcnt(5)
	v_mfma_f32_32x32x16_bf16 v[50:65], v[122:125], v[110:113], v[50:65]
	ds_read_b128 v[122:125], v131 offset:96
	s_waitcnt lgkmcnt(5)
	v_mfma_f32_32x32x16_bf16 v[34:49], v[126:129], v[110:113], v[34:49]
	ds_read_b128 v[126:129], v131 offset:6752
	s_waitcnt lgkmcnt(5)
	v_mfma_f32_32x32x16_bf16 v[82:97], v[184:187], v[98:101], v[82:97]
	ds_read_b128 v[184:187], v131 offset:13408
	s_waitcnt lgkmcnt(5)
	v_mfma_f32_32x32x16_bf16 v[66:81], v[208:211], v[98:101], v[66:81]
	ds_read_b128 v[208:211], v131 offset:20064
	s_waitcnt lgkmcnt(5)
	v_mfma_f32_32x32x16_bf16 v[50:65], v[212:215], v[98:101], v[50:65]
	ds_read_b128 v[212:215], v131 offset:128
	s_waitcnt lgkmcnt(5)
	v_mfma_f32_32x32x16_bf16 v[34:49], v[216:219], v[98:101], v[34:49]
	ds_read_b128 v[216:219], v131 offset:6784
	s_waitcnt lgkmcnt(5)
	v_mfma_f32_32x32x16_bf16 v[82:97], v[122:125], v[106:109], v[82:97]
	ds_read_b128 v[122:125], v131 offset:13440
	s_waitcnt lgkmcnt(5)
	v_mfma_f32_32x32x16_bf16 v[66:81], v[126:129], v[106:109], v[66:81]
	ds_read_b128 v[126:129], v131 offset:20096
	s_waitcnt lgkmcnt(5)
	v_mfma_f32_32x32x16_bf16 v[50:65], v[184:187], v[106:109], v[50:65]
	ds_read_b128 v[184:187], v131 offset:160
	s_waitcnt lgkmcnt(5)
	v_mfma_f32_32x32x16_bf16 v[34:49], v[208:211], v[106:109], v[34:49]
	ds_read_b128 v[208:211], v131 offset:6816
	s_waitcnt lgkmcnt(5)
	v_mfma_f32_32x32x16_bf16 v[82:97], v[212:215], v[118:121], v[82:97]
	ds_read_b128 v[212:215], v131 offset:13472
	s_waitcnt lgkmcnt(5)
	v_mfma_f32_32x32x16_bf16 v[66:81], v[216:219], v[118:121], v[66:81]
	ds_read_b128 v[216:219], v131 offset:20128
	s_waitcnt lgkmcnt(5)
	v_mfma_f32_32x32x16_bf16 v[50:65], v[122:125], v[118:121], v[50:65]
	s_waitcnt lgkmcnt(4)
	v_mfma_f32_32x32x16_bf16 v[34:49], v[126:129], v[118:121], v[34:49]
	s_waitcnt lgkmcnt(3)
	v_mfma_f32_32x32x16_bf16 v[82:97], v[184:187], v[114:117], v[82:97]
	s_waitcnt lgkmcnt(2)
	v_mfma_f32_32x32x16_bf16 v[66:81], v[208:211], v[114:117], v[66:81]
	s_waitcnt lgkmcnt(1)
	v_mfma_f32_32x32x16_bf16 v[50:65], v[212:215], v[114:117], v[50:65]
	s_waitcnt lgkmcnt(0)
	v_mfma_f32_32x32x16_bf16 v[34:49], v[216:219], v[114:117], v[34:49]
	s_barrier
	s_setprio 1
	ds_read2_b64 v[122:125], v173 offset1:2
	ds_read2_b64 v[126:129], v155 offset0:32 offset1:34
	ds_read2_b64 v[184:187], v173 offset0:4 offset1:6
	ds_read2_b64 v[208:211], v155 offset0:36 offset1:38
	ds_read2_b64 v[212:215], v173 offset0:8 offset1:10
	ds_read2_b64 v[216:219], v155 offset0:40 offset1:42
	v_exp_f32_e32 v82, v82
	v_exp_f32_e32 v83, v83
	v_exp_f32_e32 v84, v84
	v_exp_f32_e32 v85, v85
	v_exp_f32_e32 v86, v86
	v_exp_f32_e32 v87, v87
	v_exp_f32_e32 v88, v88
	v_exp_f32_e32 v89, v89
	v_add_f32_e32 v1, v82, v1
	v_add_f32_e32 v239, v83, v239
	v_add_f32_e32 v1, v84, v1
	v_add_f32_e32 v239, v85, v239
	v_add_f32_e32 v1, v86, v1
	v_add_f32_e32 v239, v87, v239
	v_add_f32_e32 v1, v88, v1
	v_add_f32_e32 v239, v89, v239
	v_cvt_pk_bf16_f32 v82, v82, v83
	v_cvt_pk_bf16_f32 v83, v84, v85
	v_cvt_pk_bf16_f32 v84, v86, v87
	v_cvt_pk_bf16_f32 v85, v88, v89
	s_waitcnt lgkmcnt(4)
	v_exp_f32_e32 v90, v90
	v_exp_f32_e32 v91, v91
	v_exp_f32_e32 v92, v92
	v_exp_f32_e32 v93, v93
	v_mfma_f32_32x32x16_bf16 v[18:33], v[122:125], v[82:85], v[18:33]
	v_exp_f32_e32 v94, v94
	v_exp_f32_e32 v95, v95
	v_exp_f32_e32 v96, v96
	v_exp_f32_e32 v97, v97
	v_mfma_f32_32x32x16_bf16 v[2:17], v[126:129], v[82:85], v[2:17]
	ds_read2_b64 v[122:125], v173 offset0:12 offset1:14
	ds_read2_b64 v[126:129], v155 offset0:44 offset1:46
	v_add_f32_e32 v1, v90, v1
	v_add_f32_e32 v239, v91, v239
	v_add_f32_e32 v1, v92, v1
	v_add_f32_e32 v239, v93, v239
	v_add_f32_e32 v1, v94, v1
	v_add_f32_e32 v239, v95, v239
	v_add_f32_e32 v1, v96, v1
	v_add_f32_e32 v239, v97, v239
	v_cvt_pk_bf16_f32 v90, v90, v91
	v_cvt_pk_bf16_f32 v91, v92, v93
	v_cvt_pk_bf16_f32 v92, v94, v95
	v_cvt_pk_bf16_f32 v93, v96, v97
	s_waitcnt lgkmcnt(4)
	v_exp_f32_e32 v66, v66
	v_exp_f32_e32 v67, v67
	v_exp_f32_e32 v68, v68
	v_exp_f32_e32 v69, v69
	v_mfma_f32_32x32x16_bf16 v[18:33], v[184:187], v[90:93], v[18:33]
	v_exp_f32_e32 v70, v70
	v_exp_f32_e32 v71, v71
	v_exp_f32_e32 v72, v72
	v_exp_f32_e32 v73, v73
	v_mfma_f32_32x32x16_bf16 v[2:17], v[208:211], v[90:93], v[2:17]
	ds_read2_b64 v[184:187], v173 offset0:16 offset1:18
	ds_read2_b64 v[208:211], v155 offset0:48 offset1:50
	v_add_f32_e32 v1, v66, v1
	v_add_f32_e32 v239, v67, v239
	v_add_f32_e32 v1, v68, v1
	v_add_f32_e32 v239, v69, v239
	v_add_f32_e32 v1, v70, v1
	v_add_f32_e32 v239, v71, v239
	v_add_f32_e32 v1, v72, v1
	v_add_f32_e32 v239, v73, v239
	v_cvt_pk_bf16_f32 v66, v66, v67
	v_cvt_pk_bf16_f32 v67, v68, v69
	v_cvt_pk_bf16_f32 v68, v70, v71
	v_cvt_pk_bf16_f32 v69, v72, v73
	s_waitcnt lgkmcnt(4)
	v_exp_f32_e32 v74, v74
	v_exp_f32_e32 v75, v75
	v_exp_f32_e32 v76, v76
	v_exp_f32_e32 v77, v77
	v_mfma_f32_32x32x16_bf16 v[18:33], v[212:215], v[66:69], v[18:33]
	v_exp_f32_e32 v78, v78
	v_exp_f32_e32 v79, v79
	v_exp_f32_e32 v80, v80
	v_exp_f32_e32 v81, v81
	v_mfma_f32_32x32x16_bf16 v[2:17], v[216:219], v[66:69], v[2:17]
	ds_read2_b64 v[212:215], v173 offset0:20 offset1:22
	ds_read2_b64 v[216:219], v155 offset0:52 offset1:54
	v_add_f32_e32 v1, v74, v1
	v_add_f32_e32 v239, v75, v239
	v_add_f32_e32 v1, v76, v1
	v_add_f32_e32 v239, v77, v239
	v_add_f32_e32 v1, v78, v1
	v_add_f32_e32 v239, v79, v239
	v_add_f32_e32 v1, v80, v1
	v_add_f32_e32 v239, v81, v239
	v_cvt_pk_bf16_f32 v74, v74, v75
	v_cvt_pk_bf16_f32 v75, v76, v77
	v_cvt_pk_bf16_f32 v76, v78, v79
	v_cvt_pk_bf16_f32 v77, v80, v81
	s_waitcnt lgkmcnt(4)
	v_exp_f32_e32 v50, v50
	v_exp_f32_e32 v51, v51
	v_exp_f32_e32 v52, v52
	v_exp_f32_e32 v53, v53
	v_mfma_f32_32x32x16_bf16 v[18:33], v[122:125], v[74:77], v[18:33]
	v_exp_f32_e32 v54, v54
	v_exp_f32_e32 v55, v55
	v_exp_f32_e32 v56, v56
	v_exp_f32_e32 v57, v57
	v_mfma_f32_32x32x16_bf16 v[2:17], v[126:129], v[74:77], v[2:17]
	ds_read2_b64 v[122:125], v173 offset0:24 offset1:26
	ds_read2_b64 v[126:129], v155 offset0:56 offset1:58
	v_lshl_add_u64 v[220:221], s[78:79], 0, v[182:183]
	v_lshl_add_u64 v[222:223], s[78:79], 0, v[180:181]
	v_lshl_add_u64 v[252:253], s[78:79], 0, v[178:179]
	global_load_dwordx4 v[224:227], v[220:221], off
	global_load_dwordx4 v[228:231], v[222:223], off
	global_load_dwordx4 v[232:235], v[252:253], off
	v_add_f32_e32 v1, v50, v1
	v_add_f32_e32 v239, v51, v239
	v_add_f32_e32 v1, v52, v1
	v_add_f32_e32 v239, v53, v239
	v_add_f32_e32 v1, v54, v1
	v_add_f32_e32 v239, v55, v239
	v_add_f32_e32 v1, v56, v1
	v_add_f32_e32 v239, v57, v239
	v_cvt_pk_bf16_f32 v50, v50, v51
	v_cvt_pk_bf16_f32 v51, v52, v53
	v_cvt_pk_bf16_f32 v52, v54, v55
	v_cvt_pk_bf16_f32 v53, v56, v57
	s_waitcnt lgkmcnt(4)
	v_exp_f32_e32 v58, v58
	v_exp_f32_e32 v59, v59
	v_exp_f32_e32 v60, v60
	v_exp_f32_e32 v61, v61
	v_mfma_f32_32x32x16_bf16 v[18:33], v[184:187], v[50:53], v[18:33]
	v_exp_f32_e32 v62, v62
	v_exp_f32_e32 v63, v63
	v_exp_f32_e32 v64, v64
	v_exp_f32_e32 v65, v65
	v_mfma_f32_32x32x16_bf16 v[2:17], v[208:211], v[50:53], v[2:17]
	ds_read2_b64 v[184:187], v173 offset0:28 offset1:30
	ds_read2_b64 v[208:211], v155 offset0:60 offset1:62
	v_add_f32_e32 v1, v58, v1
	v_add_f32_e32 v239, v59, v239
	v_add_f32_e32 v1, v60, v1
	v_add_f32_e32 v239, v61, v239
	v_add_f32_e32 v1, v62, v1
	v_add_f32_e32 v239, v63, v239
	v_add_f32_e32 v1, v64, v1
	v_add_f32_e32 v239, v65, v239
	v_cvt_pk_bf16_f32 v58, v58, v59
	v_cvt_pk_bf16_f32 v59, v60, v61
	v_cvt_pk_bf16_f32 v60, v62, v63
	v_cvt_pk_bf16_f32 v61, v64, v65
	s_waitcnt lgkmcnt(4)
	v_exp_f32_e32 v34, v34
	v_exp_f32_e32 v35, v35
	v_exp_f32_e32 v36, v36
	v_exp_f32_e32 v37, v37
	v_mfma_f32_32x32x16_bf16 v[18:33], v[212:215], v[58:61], v[18:33]
	v_exp_f32_e32 v38, v38
	v_exp_f32_e32 v39, v39
	v_exp_f32_e32 v40, v40
	v_exp_f32_e32 v41, v41
	v_mfma_f32_32x32x16_bf16 v[2:17], v[216:219], v[58:61], v[2:17]
	v_lshl_add_u64 v[174:175], v[174:175], 0, s[6:7]
	v_lshl_add_u64 v[176:177], v[176:177], 0, s[6:7]
	v_lshl_add_u64 v[178:179], v[178:179], 0, s[8:9]
	v_lshl_add_u64 v[180:181], v[180:181], 0, s[8:9]
	v_lshl_add_u64 v[182:183], v[182:183], 0, s[8:9]
	v_add_f32_e32 v1, v34, v1
	v_add_f32_e32 v239, v35, v239
	v_add_f32_e32 v1, v36, v1
	v_add_f32_e32 v239, v37, v239
	v_add_f32_e32 v1, v38, v1
	v_add_f32_e32 v239, v39, v239
	v_add_f32_e32 v1, v40, v1
	v_add_f32_e32 v239, v41, v239
	v_cvt_pk_bf16_f32 v34, v34, v35
	v_cvt_pk_bf16_f32 v35, v36, v37
	v_cvt_pk_bf16_f32 v36, v38, v39
	v_cvt_pk_bf16_f32 v37, v40, v41
	s_waitcnt lgkmcnt(2)
	v_exp_f32_e32 v42, v42
	v_exp_f32_e32 v43, v43
	v_exp_f32_e32 v44, v44
	v_exp_f32_e32 v45, v45
	v_mfma_f32_32x32x16_bf16 v[18:33], v[122:125], v[34:37], v[18:33]
	v_exp_f32_e32 v46, v46
	v_exp_f32_e32 v47, v47
	v_exp_f32_e32 v48, v48
	v_exp_f32_e32 v49, v49
	v_mfma_f32_32x32x16_bf16 v[2:17], v[126:129], v[34:37], v[2:17]
	v_add_f32_e32 v1, v42, v1
	v_add_f32_e32 v239, v43, v239
	v_add_f32_e32 v1, v44, v1
	v_add_f32_e32 v239, v45, v239
	v_add_f32_e32 v1, v46, v1
	v_add_f32_e32 v239, v47, v239
	v_add_f32_e32 v1, v48, v1
	v_add_f32_e32 v239, v49, v239
	v_cvt_pk_bf16_f32 v42, v42, v43
	v_cvt_pk_bf16_f32 v43, v44, v45
	v_cvt_pk_bf16_f32 v44, v46, v47
	v_cvt_pk_bf16_f32 v45, v48, v49
	s_waitcnt lgkmcnt(0)
	s_nop 0
	v_mfma_f32_32x32x16_bf16 v[18:33], v[184:187], v[42:45], v[18:33]
	v_mfma_f32_32x32x16_bf16 v[2:17], v[208:211], v[42:45], v[2:17]
	s_add_i32 s13, s13, 1
	v_add_u32_e32 v220, s0, v200
	v_add3_u32 v221, v220, v202, s44
	v_add3_u32 v220, v220, v203, s44
	s_waitcnt vmcnt(3)
	ds_write2_b64 v221, v[240:241], v[242:243] offset1:1
	ds_write2_b64 v220, v[244:245], v[246:247] offset1:1
	s_cmp_eq_u32 s34, s13
	s_waitcnt lgkmcnt(0)
	s_barrier
	s_cbranch_scc1 .Lmf_final
	s_branch .Lmf_loop
.Lmf_final:
	s_setprio 0
	v_add_f32_e32 v1, v1, v239
	v_add3_u32 v133, s0, v132, v204
	ds_read_b128 v[34:37], v133
	ds_read_b128 v[122:125], v133 offset:32
	s_waitcnt lgkmcnt(1)
	v_mfma_f32_32x32x16_bf16 v[82:97], v[34:37], v[102:105], 0
	ds_read_b128 v[34:37], v133 offset:6656
	ds_read_b128 v[126:129], v133 offset:6688
	s_waitcnt lgkmcnt(1)
	v_mfma_f32_32x32x16_bf16 v[66:81], v[34:37], v[102:105], 0
	ds_read_b128 v[34:37], v133 offset:13312
	ds_read_b128 v[174:177], v133 offset:13344
	s_waitcnt lgkmcnt(1)
	v_mfma_f32_32x32x16_bf16 v[50:65], v[34:37], v[102:105], 0
	ds_read_b128 v[34:37], v133 offset:19968
	ds_read_b128 v[178:181], v133 offset:20000
	s_waitcnt lgkmcnt(1)
	v_mfma_f32_32x32x16_bf16 v[34:49], v[34:37], v[102:105], 0
	v_mfma_f32_32x32x16_bf16 v[82:97], v[122:125], v[110:113], v[82:97]
	v_mfma_f32_32x32x16_bf16 v[66:81], v[126:129], v[110:113], v[66:81]
	v_mfma_f32_32x32x16_bf16 v[50:65], v[174:177], v[110:113], v[50:65]
	s_waitcnt lgkmcnt(0)
	v_mfma_f32_32x32x16_bf16 v[34:49], v[178:181], v[110:113], v[34:49]
	ds_read_b128 v[102:105], v133 offset:64
	ds_read_b128 v[110:113], v133 offset:96
	s_waitcnt lgkmcnt(1)
	v_mfma_f32_32x32x16_bf16 v[82:97], v[102:105], v[98:101], v[82:97]
	ds_read_b128 v[102:105], v133 offset:6720
	ds_read_b128 v[122:125], v133 offset:6752
	s_waitcnt lgkmcnt(1)
	v_mfma_f32_32x32x16_bf16 v[66:81], v[102:105], v[98:101], v[66:81]
	ds_read_b128 v[102:105], v133 offset:13376
	ds_read_b128 v[126:129], v133 offset:13408
	s_waitcnt lgkmcnt(1)
	v_mfma_f32_32x32x16_bf16 v[50:65], v[102:105], v[98:101], v[50:65]
	ds_read_b128 v[102:105], v133 offset:20032
	ds_read_b128 v[174:177], v133 offset:20064
	v_mfma_f32_32x32x16_bf16 v[82:97], v[110:113], v[106:109], v[82:97]
	s_waitcnt lgkmcnt(1)
	v_mfma_f32_32x32x16_bf16 v[34:49], v[102:105], v[98:101], v[34:49]
	ds_read_b128 v[98:101], v133 offset:128
	ds_read_b128 v[102:105], v133 offset:160
	v_mfma_f32_32x32x16_bf16 v[66:81], v[122:125], v[106:109], v[66:81]
	s_waitcnt lgkmcnt(1)
	v_mfma_f32_32x32x16_bf16 v[82:97], v[98:101], v[118:121], v[82:97]
	v_mfma_f32_32x32x16_bf16 v[50:65], v[126:129], v[106:109], v[50:65]
	v_mfma_f32_32x32x16_bf16 v[34:49], v[174:177], v[106:109], v[34:49]
	ds_read_b128 v[98:101], v133 offset:6784
	ds_read_b128 v[106:109], v133 offset:6816
	s_waitcnt lgkmcnt(1)
	v_mfma_f32_32x32x16_bf16 v[66:81], v[98:101], v[118:121], v[66:81]
	ds_read_b128 v[98:101], v133 offset:13440
	ds_read_b128 v[110:113], v133 offset:13472
	v_mfma_f32_32x32x16_bf16 v[82:97], v[102:105], v[114:117], v[82:97]
	s_waitcnt lgkmcnt(1)
	v_mfma_f32_32x32x16_bf16 v[50:65], v[98:101], v[118:121], v[50:65]
	s_nop 9
	ds_read_b128 v[98:101], v133 offset:20096
	ds_read_b128 v[102:105], v133 offset:20128
	v_mfma_f32_32x32x16_bf16 v[66:81], v[106:109], v[114:117], v[66:81]
	s_nop 6
	s_waitcnt lgkmcnt(2)
	v_mfma_f32_32x32x16_bf16 v[50:65], v[110:113], v[114:117], v[50:65]
	s_waitcnt lgkmcnt(1)
	v_mfma_f32_32x32x16_bf16 v[34:49], v[98:101], v[118:121], v[34:49]
	s_nop 2
	s_waitcnt lgkmcnt(0)
	v_mfma_f32_32x32x16_bf16 v[34:49], v[102:105], v[114:117], v[34:49]
	s_nop 10
	s_barrier
	s_setprio 1
	v_exp_f32_e32 v99, v66
	v_exp_f32_e32 v100, v67
	v_exp_f32_e32 v101, v68
	v_exp_f32_e32 v102, v69
	v_exp_f32_e32 v103, v70
	v_exp_f32_e32 v104, v71
	v_exp_f32_e32 v105, v72
	v_exp_f32_e32 v106, v73
	v_exp_f32_e32 v74, v74
	v_exp_f32_e32 v75, v75
	v_exp_f32_e32 v76, v76
	v_exp_f32_e32 v77, v77
	v_exp_f32_e32 v78, v78
	v_exp_f32_e32 v79, v79
	v_add3_u32 v70, s0, v189, v205
	v_exp_f32_e32 v80, v80
	v_add_u32_e32 v109, 0x6800, v70
	v_exp_f32_e32 v81, v81
	ds_read2_b64 v[66:69], v109 offset1:2
	v_add_u32_e32 v112, 0x8800, v70
	v_exp_f32_e32 v82, v82
	v_exp_f32_e32 v83, v83
	v_exp_f32_e32 v84, v84
	v_exp_f32_e32 v85, v85
	v_exp_f32_e32 v86, v86
	v_exp_f32_e32 v87, v87
	v_exp_f32_e32 v88, v88
	v_exp_f32_e32 v89, v89
	ds_read2_b64 v[70:73], v112 offset0:32 offset1:34
	v_exp_f32_e32 v107, v50
	v_exp_f32_e32 v108, v51
	v_exp_f32_e32 v110, v52
	v_mov_b32_e32 v111, v53
	v_cvt_pk_bf16_f32 v50, v82, v83
	v_cvt_pk_bf16_f32 v51, v84, v85
	v_cvt_pk_bf16_f32 v52, v86, v87
	v_cvt_pk_bf16_f32 v53, v88, v89
	v_exp_f32_e32 v113, v54
	s_waitcnt lgkmcnt(1)
	v_mfma_f32_32x32x16_bf16 v[18:33], v[66:69], v[50:53], v[18:33]
	ds_read2_b64 v[66:69], v109 offset0:4 offset1:6
	v_exp_f32_e32 v114, v55
	v_exp_f32_e32 v90, v90
	v_exp_f32_e32 v91, v91
	v_exp_f32_e32 v92, v92
	v_exp_f32_e32 v93, v93
	v_exp_f32_e32 v94, v94
	v_exp_f32_e32 v95, v95
	v_exp_f32_e32 v96, v96
	v_exp_f32_e32 v97, v97
	s_waitcnt lgkmcnt(1)
	v_mfma_f32_32x32x16_bf16 v[2:17], v[70:73], v[50:53], v[2:17]
	v_exp_f32_e32 v70, v56
	v_mov_b32_e32 v71, v57
	ds_read2_b64 v[54:57], v112 offset0:36 offset1:38
	v_cvt_pk_bf16_f32 v50, v90, v91
	v_cvt_pk_bf16_f32 v51, v92, v93
	v_cvt_pk_bf16_f32 v52, v94, v95
	v_cvt_pk_bf16_f32 v53, v96, v97
	v_exp_f32_e32 v72, v58
	s_waitcnt lgkmcnt(1)
	v_mfma_f32_32x32x16_bf16 v[18:33], v[66:69], v[50:53], v[18:33]
	ds_read2_b64 v[66:69], v109 offset0:8 offset1:10
	v_exp_f32_e32 v73, v59
	v_exp_f32_e32 v115, v60
	v_exp_f32_e32 v111, v111
	s_waitcnt lgkmcnt(1)
	v_mfma_f32_32x32x16_bf16 v[2:17], v[54:57], v[50:53], v[2:17]
	ds_read2_b64 v[54:57], v112 offset0:40 offset1:42
	v_cvt_pk_bf16_f32 v50, v99, v100
	v_cvt_pk_bf16_f32 v51, v101, v102
	v_cvt_pk_bf16_f32 v52, v103, v104
	v_cvt_pk_bf16_f32 v53, v105, v106
	v_exp_f32_e32 v71, v71
	s_waitcnt lgkmcnt(1)
	v_mfma_f32_32x32x16_bf16 v[18:33], v[66:69], v[50:53], v[18:33]
	v_exp_f32_e32 v66, v61
	v_exp_f32_e32 v62, v62
	v_exp_f32_e32 v63, v63
	ds_read2_b64 v[58:61], v109 offset0:12 offset1:14
	v_exp_f32_e32 v67, v34
	s_waitcnt lgkmcnt(1)
	v_mfma_f32_32x32x16_bf16 v[2:17], v[54:57], v[50:53], v[2:17]
	ds_read2_b64 v[54:57], v112 offset0:44 offset1:46
	v_cvt_pk_bf16_f32 v50, v74, v75
	v_cvt_pk_bf16_f32 v51, v76, v77
	v_cvt_pk_bf16_f32 v52, v78, v79
	v_cvt_pk_bf16_f32 v53, v80, v81
	v_exp_f32_e32 v68, v35
	s_waitcnt lgkmcnt(1)
	v_mfma_f32_32x32x16_bf16 v[18:33], v[58:61], v[50:53], v[18:33]
	ds_read2_b64 v[58:61], v109 offset0:16 offset1:18
	v_exp_f32_e32 v69, v36
	v_cvt_pk_bf16_f32 v34, v107, v108
	v_cvt_pk_bf16_f32 v35, v110, v111
	v_cvt_pk_bf16_f32 v36, v113, v114
	s_waitcnt lgkmcnt(1)
	v_mfma_f32_32x32x16_bf16 v[2:17], v[54:57], v[50:53], v[2:17]
	ds_read2_b64 v[50:53], v112 offset0:48 offset1:50
	v_mov_b32_e32 v54, v37
	v_cvt_pk_bf16_f32 v37, v70, v71
	v_exp_f32_e32 v64, v64
	v_exp_f32_e32 v65, v65
	s_waitcnt lgkmcnt(1)
	v_mfma_f32_32x32x16_bf16 v[18:33], v[58:61], v[34:37], v[18:33]
	v_exp_f32_e32 v58, v54
	v_exp_f32_e32 v59, v38
	ds_read2_b64 v[54:57], v109 offset0:20 offset1:22
	v_exp_f32_e32 v60, v39
	v_exp_f32_e32 v61, v40
	s_waitcnt lgkmcnt(1)
	v_mfma_f32_32x32x16_bf16 v[2:17], v[50:53], v[34:37], v[2:17]
	v_mov_b32_e32 v50, v41
	ds_read2_b64 v[38:41], v112 offset0:52 offset1:54
	v_cvt_pk_bf16_f32 v34, v72, v73
	v_cvt_pk_bf16_f32 v35, v115, v66
	v_cvt_pk_bf16_f32 v36, v62, v63
	v_cvt_pk_bf16_f32 v37, v64, v65
	s_waitcnt lgkmcnt(1)
	s_nop 0
	v_mfma_f32_32x32x16_bf16 v[18:33], v[54:57], v[34:37], v[18:33]
	v_exp_f32_e32 v54, v50
	ds_read2_b64 v[50:53], v109 offset0:24 offset1:26
	v_exp_f32_e32 v55, v42
	v_exp_f32_e32 v56, v43
	v_exp_f32_e32 v57, v44
	s_waitcnt lgkmcnt(1)
	v_mfma_f32_32x32x16_bf16 v[2:17], v[38:41], v[34:37], v[2:17]
	ds_read2_b64 v[38:41], v112 offset0:56 offset1:58
	v_cvt_pk_bf16_f32 v34, v67, v68
	v_cvt_pk_bf16_f32 v35, v69, v58
	v_cvt_pk_bf16_f32 v36, v59, v60
	v_cvt_pk_bf16_f32 v37, v61, v54
	v_exp_f32_e32 v48, v48
	s_lshl_b64 s[10:11], s[10:11], 10
	s_waitcnt lgkmcnt(1)
	v_mfma_f32_32x32x16_bf16 v[18:33], v[50:53], v[34:37], v[18:33]
	v_exp_f32_e32 v50, v45
	v_exp_f32_e32 v46, v46
	v_exp_f32_e32 v47, v47
	ds_read2_b64 v[42:45], v109 offset0:28 offset1:30
	s_add_u32 s0, s36, s10
	s_waitcnt lgkmcnt(1)
	v_mfma_f32_32x32x16_bf16 v[2:17], v[38:41], v[34:37], v[2:17]
	ds_read2_b64 v[38:41], v112 offset0:60 offset1:62
	v_exp_f32_e32 v49, v49
	v_cvt_pk_bf16_f32 v34, v55, v56
	v_cvt_pk_bf16_f32 v35, v57, v50
	v_cvt_pk_bf16_f32 v36, v46, v47
	v_cvt_pk_bf16_f32 v37, v48, v49
	s_addc_u32 s11, s37, s11
	s_lshl_b32 s10, s49, 7
	s_waitcnt lgkmcnt(1)
	v_mfma_f32_32x32x16_bf16 v[18:33], v[42:45], v[34:37], v[18:33]
	s_add_u32 s10, s0, s10
	s_addc_u32 s11, s11, 0
	s_waitcnt lgkmcnt(0)
	s_cmpk_lt_i32 s40, 0x100
	s_cbranch_scc0 .Lmf_fin_nobar
	s_barrier
.Lmf_fin_nobar:
	v_mfma_f32_32x32x16_bf16 v[2:17], v[38:41], v[34:37], v[2:17]
	s_branch .Lmla_fin_join

	.amdhsa_kernel _Z4mega6Params
		.amdhsa_group_segment_fixed_size 0
		.amdhsa_private_segment_fixed_size 0
		.amdhsa_kernarg_size 496
		.amdhsa_user_sgpr_count 2
		.amdhsa_user_sgpr_dispatch_ptr 0
		.amdhsa_user_sgpr_queue_ptr 0
		.amdhsa_user_sgpr_kernarg_segment_ptr 1
		.amdhsa_user_sgpr_dispatch_id 0
		.amdhsa_user_sgpr_kernarg_preload_length 0
		.amdhsa_user_sgpr_kernarg_preload_offset 0
		.amdhsa_user_sgpr_private_segment_size 0
		.amdhsa_uses_dynamic_stack 0
		.amdhsa_enable_private_segment 0
		.amdhsa_system_sgpr_workgroup_id_x 1
		.amdhsa_system_sgpr_workgroup_id_y 0
		.amdhsa_system_sgpr_workgroup_id_z 0
		.amdhsa_system_sgpr_workgroup_info 0
		.amdhsa_system_vgpr_workitem_id 0
		.amdhsa_next_free_vgpr 256
		.amdhsa_next_free_sgpr 102
		.amdhsa_accum_offset 256
		.amdhsa_reserve_vcc 1
		.amdhsa_float_round_mode_32 0
		.amdhsa_float_round_mode_16_64 0
		.amdhsa_float_denorm_mode_32 3
		.amdhsa_float_denorm_mode_16_64 3
		.amdhsa_dx10_clamp 1
		.amdhsa_ieee_mode 1
		.amdhsa_fp16_overflow 0
		.amdhsa_tg_split 0
		.amdhsa_exception_fp_ieee_invalid_op 0
		.amdhsa_exception_fp_denorm_src 0
		.amdhsa_exception_fp_ieee_div_zero 0
		.amdhsa_exception_fp_ieee_overflow 0
		.amdhsa_exception_fp_ieee_underflow 0
		.amdhsa_exception_fp_ieee_inexact 0
		.amdhsa_exception_int_div_zero 0
	.end_amdhsa_kernel

amdhsa.kernels:
  - .agpr_count:     0
    .args:
      - .offset:         0
        .size:           240
        .value_kind:     by_value
      - .offset:         240
        .size:           4
        .value_kind:     hidden_block_count_x
      - .offset:         244
        .size:           4
        .value_kind:     hidden_block_count_y
      - .offset:         248
        .size:           4
        .value_kind:     hidden_block_count_z
      - .offset:         252
        .size:           2
        .value_kind:     hidden_group_size_x
      - .offset:         254
        .size:           2
        .value_kind:     hidden_group_size_y
      - .offset:         256
        .size:           2
        .value_kind:     hidden_group_size_z
      - .offset:         258
        .size:           2
        .value_kind:     hidden_remainder_x
      - .offset:         260
        .size:           2
        .value_kind:     hidden_remainder_y
      - .offset:         262
        .size:           2
        .value_kind:     hidden_remainder_z
      - .offset:         280
        .size:           8
        .value_kind:     hidden_global_offset_x
      - .offset:         288
        .size:           8
        .value_kind:     hidden_global_offset_y
      - .offset:         296
        .size:           8
        .value_kind:     hidden_global_offset_z
      - .offset:         304
        .size:           2
        .value_kind:     hidden_grid_dims
      - .offset:         360
        .size:           4
        .value_kind:     hidden_dynamic_lds_size
    .group_segment_fixed_size: 0
    .kernarg_segment_align: 8
    .kernarg_segment_size: 496
    .language:       OpenCL C
    .language_version:
      - 2
      - 0
    .max_flat_workgroup_size: 512
    .name:           _Z4mega6Params
    .private_segment_fixed_size: 0
    .sgpr_count:     108
    .sgpr_spill_count: 60
    .symbol:         _Z4mega6Params.kd
    .uniform_work_group_size: 1
    .uses_dynamic_stack: false
    .vgpr_count:     256
    .vgpr_spill_count: 0
    .wavefront_size: 64
